# FFN-down fused LayerNorm epilogue: residual tile loads de-serialised (32 loads issued in one batch into dead K-loop fragment registers, counted vmcnt waits) instead of 8 load-wait-use round trips
# speedup vs baseline: 1.0137x; 1.0030x over previous
; __device__ __forceinline__ float bf_lo(unsigned w) { return __uint_as_float(w << 16); }
; __device__ __forceinline__ float bf_hi(unsigned w) { return __uint_as_float(w & 0xffff0000u); }
;     __device__ __forceinline__ void operator()(pg8::f32x4 (&acc)[2][2][4][2], const pg8::Unit& u, int wr, int wc, int fr, int fq) const {
;         typedef float f32x2v __attribute__((ext_vector_type(2)));
;         const int wid = wr * 4 + wc, lane = fq * 16 + fr;
;         const size_t off0 = ((size_t)u.pm * 256 + wr * 64 + fr) * DM + (size_t)u.pn * 256 + wc * 32 + 4 * fq;
; #pragma unroll
;         for (int ai = 0; ai < 2; ++ai)
; #pragma unroll
;             for (int m = 0; m < 4; ++m) {
; #pragma unroll
;                 for (int bj = 0; bj < 2; ++bj)
; #pragma unroll
;                     for (int n = 0; n < 2; ++n) { const size_t o_ = off0 + (size_t)(ai * 128 + m * 16) * DM + bj * 128 + n * 16; pg8::f32x4 bs;
;                         if (BASE_BF16) { const v2u w = *(const v2u*)((const bf16*)basev + o_); bs = (pg8::f32x4){pg8::bf_lo(w.x), pg8::bf_hi(w.x), pg8::bf_lo(w.y), pg8::bf_hi(w.y)}; }
;                         else bs = *(const pg8::f32x4*)((const float*)basev + o_);
;                         acc[ai][bj][m][n] = bs * ALPHA + acc[ai][bj][m][n]; }
;                 asm volatile("" : "+v"(acc[ai][0][m][0]), "+v"(acc[ai][0][m][1]), "+v"(acc[ai][1][m][0]), "+v"(acc[ai][1][m][1]));
;                 if (m & 1) asm volatile("" ::: "memory"); }
.LBB0_1817:
	s_ashr_i32 s11, s10, 31
	s_ashr_i32 s51, s50, 31
	s_lshl_b64 s[54:55], s[10:11], 18
	s_lshl_b64 s[56:57], s[50:51], 8
	s_add_u32 s54, s54, s56
	s_addc_u32 s55, s55, s57
	v_lshl_add_u64 v[132:133], s[54:55], 0, v[152:153]
	v_lshl_add_u64 v[128:129], v[132:133], 1, s[18:19]
	global_load_dwordx2 v[192:193], v[128:129], off
	global_load_dwordx2 v[194:195], v[128:129], off offset:32
	global_load_dwordx2 v[196:197], v[128:129], off offset:256
	global_load_dwordx2 v[198:199], v[128:129], off offset:288
	v_add_co_u32_e32 v140, vcc, s73, v128
	s_nop 1
	v_addc_co_u32_e32 v141, vcc, 0, v129, vcc
	global_load_dwordx2 v[200:201], v[140:141], off
	global_load_dwordx2 v[202:203], v[140:141], off offset:32
	global_load_dwordx2 v[204:205], v[140:141], off offset:256
	global_load_dwordx2 v[206:207], v[140:141], off offset:288
	v_add_co_u32_e32 v140, vcc, s67, v128
	s_nop 1
	v_addc_co_u32_e32 v141, vcc, 0, v129, vcc
	global_load_dwordx2 v[208:209], v[140:141], off
	global_load_dwordx2 v[210:211], v[140:141], off offset:32
	global_load_dwordx2 v[212:213], v[140:141], off offset:256
	global_load_dwordx2 v[214:215], v[140:141], off offset:288
	v_add_co_u32_e32 v140, vcc, s72, v128
	s_nop 1
	v_addc_co_u32_e32 v141, vcc, 0, v129, vcc
	global_load_dwordx2 v[216:217], v[140:141], off
	global_load_dwordx2 v[218:219], v[140:141], off offset:32
	global_load_dwordx2 v[220:221], v[140:141], off offset:256
	global_load_dwordx2 v[222:223], v[140:141], off offset:288
	v_add_co_u32_e32 v140, vcc, s78, v128
	s_nop 1
	v_addc_co_u32_e32 v141, vcc, 0, v129, vcc
	global_load_dwordx2 v[224:225], v[140:141], off
	global_load_dwordx2 v[226:227], v[140:141], off offset:32
	global_load_dwordx2 v[228:229], v[140:141], off offset:256
	global_load_dwordx2 v[230:231], v[140:141], off offset:288
	v_add_co_u32_e32 v140, vcc, s79, v128
	s_nop 1
	v_addc_co_u32_e32 v141, vcc, 0, v129, vcc
	global_load_dwordx2 v[232:233], v[140:141], off
	global_load_dwordx2 v[234:235], v[140:141], off offset:32
	global_load_dwordx2 v[236:237], v[140:141], off offset:256
	global_load_dwordx2 v[238:239], v[140:141], off offset:288
	v_add_co_u32_e32 v140, vcc, s80, v128
	s_nop 1
	v_addc_co_u32_e32 v141, vcc, 0, v129, vcc
	global_load_dwordx2 v[240:241], v[140:141], off
	global_load_dwordx2 v[242:243], v[140:141], off offset:32
	global_load_dwordx2 v[244:245], v[140:141], off offset:256
	global_load_dwordx2 v[246:247], v[140:141], off offset:288
	v_add_co_u32_e32 v140, vcc, s81, v128
	s_nop 1
	v_addc_co_u32_e32 v141, vcc, 0, v129, vcc
	global_load_dwordx2 v[248:249], v[140:141], off
	global_load_dwordx2 v[250:251], v[140:141], off offset:32
	global_load_dwordx2 v[252:253], v[140:141], off offset:256
	global_load_dwordx2 v[254:255], v[140:141], off offset:288
	v_add_co_u32_e32 v140, vcc, s73, v128
	s_waitcnt vmcnt(28)
	v_lshlrev_b32_e32 v142, 16, v192
	v_and_b32_e32 v143, 0xffff0000, v192
	v_lshlrev_b32_e32 v130, 16, v193
	v_and_b32_e32 v131, 0xffff0000, v193
	v_lshlrev_b32_e32 v144, 16, v194
	v_and_b32_e32 v145, 0xffff0000, v194
	v_lshlrev_b32_e32 v134, 16, v195
	v_and_b32_e32 v135, 0xffff0000, v195
	v_lshlrev_b32_e32 v146, 16, v196
	v_and_b32_e32 v147, 0xffff0000, v196
	v_lshlrev_b32_e32 v136, 16, v197
	v_and_b32_e32 v137, 0xffff0000, v197
	v_lshlrev_b32_e32 v162, 16, v198
	v_and_b32_e32 v163, 0xffff0000, v198
	v_lshlrev_b32_e32 v138, 16, v199
	v_and_b32_e32 v139, 0xffff0000, v199
	v_addc_co_u32_e32 v141, vcc, 0, v129, vcc
	v_pk_fma_f32 v[58:59], v[130:131], s[38:39], v[58:59] op_sel_hi:[1,0,1]
	v_pk_fma_f32 v[56:57], v[142:143], s[38:39], v[56:57] op_sel_hi:[1,0,1]
	v_pk_fma_f32 v[34:35], v[134:135], s[38:39], v[34:35] op_sel_hi:[1,0,1]
	v_pk_fma_f32 v[32:33], v[144:145], s[38:39], v[32:33] op_sel_hi:[1,0,1]
	v_pk_fma_f32 v[14:15], v[136:137], s[38:39], v[14:15] op_sel_hi:[1,0,1]
	v_pk_fma_f32 v[12:13], v[146:147], s[38:39], v[12:13] op_sel_hi:[1,0,1]
	v_pk_fma_f32 v[2:3], v[138:139], s[38:39], v[2:3] op_sel_hi:[1,0,1]
	v_pk_fma_f32 v[0:1], v[162:163], s[38:39], v[0:1] op_sel_hi:[1,0,1]
	s_nop 0
	v_add_co_u32_e32 v140, vcc, s67, v128
	s_waitcnt vmcnt(27)
	v_lshlrev_b32_e32 v142, 16, v200
	v_and_b32_e32 v143, 0xffff0000, v200
	v_lshlrev_b32_e32 v130, 16, v201
	v_and_b32_e32 v131, 0xffff0000, v201
	s_waitcnt vmcnt(26)
	v_lshlrev_b32_e32 v144, 16, v202
	v_and_b32_e32 v145, 0xffff0000, v202
	v_lshlrev_b32_e32 v134, 16, v203
	v_and_b32_e32 v135, 0xffff0000, v203
	s_waitcnt vmcnt(25)
	v_lshlrev_b32_e32 v146, 16, v204
	v_and_b32_e32 v147, 0xffff0000, v204
	v_lshlrev_b32_e32 v136, 16, v205
	v_and_b32_e32 v137, 0xffff0000, v205
	s_waitcnt vmcnt(24)
	v_lshlrev_b32_e32 v162, 16, v206
	v_and_b32_e32 v163, 0xffff0000, v206
	v_lshlrev_b32_e32 v138, 16, v207
	v_and_b32_e32 v139, 0xffff0000, v207
	v_pk_fma_f32 v[74:75], v[130:131], s[38:39], v[74:75] op_sel_hi:[1,0,1]
	v_pk_fma_f32 v[72:73], v[142:143], s[38:39], v[72:73] op_sel_hi:[1,0,1]
	v_pk_fma_f32 v[46:47], v[134:135], s[38:39], v[46:47] op_sel_hi:[1,0,1]
	v_pk_fma_f32 v[44:45], v[144:145], s[38:39], v[44:45] op_sel_hi:[1,0,1]
	v_pk_fma_f32 v[22:23], v[136:137], s[38:39], v[22:23] op_sel_hi:[1,0,1]
	v_pk_fma_f32 v[20:21], v[146:147], s[38:39], v[20:21] op_sel_hi:[1,0,1]
	v_pk_fma_f32 v[6:7], v[138:139], s[38:39], v[6:7] op_sel_hi:[1,0,1]
	v_pk_fma_f32 v[4:5], v[162:163], s[38:39], v[4:5] op_sel_hi:[1,0,1]
	v_addc_co_u32_e32 v141, vcc, 0, v129, vcc
	v_add_co_u32_e32 v140, vcc, s72, v128
	s_waitcnt vmcnt(23)
	v_lshlrev_b32_e32 v142, 16, v208
	v_and_b32_e32 v143, 0xffff0000, v208
	v_lshlrev_b32_e32 v130, 16, v209
	v_and_b32_e32 v131, 0xffff0000, v209
	s_waitcnt vmcnt(22)
	v_lshlrev_b32_e32 v144, 16, v210
	v_and_b32_e32 v145, 0xffff0000, v210
	v_lshlrev_b32_e32 v134, 16, v211
	v_and_b32_e32 v135, 0xffff0000, v211
	s_waitcnt vmcnt(21)
; __device__ __forceinline__ float bf_lo(unsigned w) { return __uint_as_float(w << 16); }
; __device__ __forceinline__ float bf_hi(unsigned w) { return __uint_as_float(w & 0xffff0000u); }
;     __device__ __forceinline__ bool run(const pg8::f32x4 (&v)[2][2][4][2], const pg8::Unit& u, int wr, int wc, int fr, int fq, LAS unsigned char* sl, int wid, int lane) const {
;     ...
;         for (int ai = 0; ai < 2; ++ai)
; #pragma unroll
;             for (int m = 0; m < 4; ++m) {
;                 float s = 0.f;
; #pragma unroll
;                 for (int bj = 0; bj < 2; ++bj)
; #pragma unroll
;                     for (int n = 0; n < 2; ++n) { const pg8::f32x4 x = v[ai][bj][m][n]; s += (x[0] + x[1]) + (x[2] + x[3]); }
;                 s += __shfl_xor(s, 16); s += __shfl_xor(s, 32);
;     __device__ __forceinline__ void operator()(pg8::f32x4 (&acc)[2][2][4][2], const pg8::Unit& u, int wr, int wc, int fr, int fq) const {
;     ...
;         for (int ai = 0; ai < 2; ++ai)
; #pragma unroll
;             for (int m = 0; m < 4; ++m) {
; #pragma unroll
;                 for (int bj = 0; bj < 2; ++bj)
; #pragma unroll
;                     for (int n = 0; n < 2; ++n) { const size_t o_ = off0 + (size_t)(ai * 128 + m * 16) * DM + bj * 128 + n * 16; pg8::f32x4 bs;
;                         if (BASE_BF16) { const v2u w = *(const v2u*)((const bf16*)basev + o_); bs = (pg8::f32x4){pg8::bf_lo(w.x), pg8::bf_hi(w.x), pg8::bf_lo(w.y), pg8::bf_hi(w.y)}; }
;                         else bs = *(const pg8::f32x4*)((const float*)basev + o_);
;                         acc[ai][bj][m][n] = bs * ALPHA + acc[ai][bj][m][n]; }
;                 asm volatile("" : "+v"(acc[ai][0][m][0]), "+v"(acc[ai][0][m][1]), "+v"(acc[ai][1][m][0]), "+v"(acc[ai][1][m][1]));
;                 if (m & 1) asm volatile("" ::: "memory"); }
	v_lshlrev_b32_e32 v146, 16, v212
	v_and_b32_e32 v147, 0xffff0000, v212
	v_lshlrev_b32_e32 v136, 16, v213
	v_and_b32_e32 v137, 0xffff0000, v213
	s_waitcnt vmcnt(20)
	v_lshlrev_b32_e32 v162, 16, v214
	v_and_b32_e32 v163, 0xffff0000, v214
	v_lshlrev_b32_e32 v138, 16, v215
	v_and_b32_e32 v139, 0xffff0000, v215
	v_addc_co_u32_e32 v141, vcc, 0, v129, vcc
	v_pk_fma_f32 v[86:87], v[130:131], s[38:39], v[86:87] op_sel_hi:[1,0,1]
	v_pk_fma_f32 v[84:85], v[142:143], s[38:39], v[84:85] op_sel_hi:[1,0,1]
	v_pk_fma_f32 v[54:55], v[134:135], s[38:39], v[54:55] op_sel_hi:[1,0,1]
	v_pk_fma_f32 v[52:53], v[144:145], s[38:39], v[52:53] op_sel_hi:[1,0,1]
	v_pk_fma_f32 v[30:31], v[136:137], s[38:39], v[30:31] op_sel_hi:[1,0,1]
	v_pk_fma_f32 v[28:29], v[146:147], s[38:39], v[28:29] op_sel_hi:[1,0,1]
	v_pk_fma_f32 v[10:11], v[138:139], s[38:39], v[10:11] op_sel_hi:[1,0,1]
	v_pk_fma_f32 v[8:9], v[162:163], s[38:39], v[8:9] op_sel_hi:[1,0,1]
	s_nop 0
	v_add_co_u32_e32 v140, vcc, s78, v128
	s_waitcnt vmcnt(19)
	v_lshlrev_b32_e32 v142, 16, v216
	v_and_b32_e32 v143, 0xffff0000, v216
	v_lshlrev_b32_e32 v130, 16, v217
	v_and_b32_e32 v131, 0xffff0000, v217
	s_waitcnt vmcnt(18)
	v_lshlrev_b32_e32 v144, 16, v218
	v_and_b32_e32 v145, 0xffff0000, v218
	v_lshlrev_b32_e32 v134, 16, v219
	v_and_b32_e32 v135, 0xffff0000, v219
	s_waitcnt vmcnt(17)
	v_lshlrev_b32_e32 v146, 16, v220
	v_and_b32_e32 v147, 0xffff0000, v220
	v_lshlrev_b32_e32 v136, 16, v221
	v_and_b32_e32 v137, 0xffff0000, v221
	s_waitcnt vmcnt(16)
	v_lshlrev_b32_e32 v162, 16, v222
	v_and_b32_e32 v163, 0xffff0000, v222
	v_lshlrev_b32_e32 v138, 16, v223
	v_and_b32_e32 v139, 0xffff0000, v223
	v_pk_fma_f32 v[110:111], v[130:131], s[38:39], v[110:111] op_sel_hi:[1,0,1]
	v_pk_fma_f32 v[108:109], v[142:143], s[38:39], v[108:109] op_sel_hi:[1,0,1]
	v_pk_fma_f32 v[66:67], v[134:135], s[38:39], v[66:67] op_sel_hi:[1,0,1]
	v_pk_fma_f32 v[64:65], v[144:145], s[38:39], v[64:65] op_sel_hi:[1,0,1]
	v_pk_fma_f32 v[42:43], v[136:137], s[38:39], v[42:43] op_sel_hi:[1,0,1]
	v_pk_fma_f32 v[40:41], v[146:147], s[38:39], v[40:41] op_sel_hi:[1,0,1]
	v_pk_fma_f32 v[18:19], v[138:139], s[38:39], v[18:19] op_sel_hi:[1,0,1]
	v_pk_fma_f32 v[16:17], v[162:163], s[38:39], v[16:17] op_sel_hi:[1,0,1]
	v_addc_co_u32_e32 v141, vcc, 0, v129, vcc
	v_add_co_u32_e32 v140, vcc, s79, v128
	s_waitcnt vmcnt(15)
	v_lshlrev_b32_e32 v142, 16, v224
	v_and_b32_e32 v143, 0xffff0000, v224
	v_lshlrev_b32_e32 v130, 16, v225
	v_and_b32_e32 v131, 0xffff0000, v225
	s_waitcnt vmcnt(14)
	v_lshlrev_b32_e32 v144, 16, v226
	v_and_b32_e32 v145, 0xffff0000, v226
	v_lshlrev_b32_e32 v134, 16, v227
	v_and_b32_e32 v135, 0xffff0000, v227
	s_waitcnt vmcnt(13)
	v_lshlrev_b32_e32 v146, 16, v228
	v_and_b32_e32 v147, 0xffff0000, v228
	v_lshlrev_b32_e32 v136, 16, v229
	v_and_b32_e32 v137, 0xffff0000, v229
	s_waitcnt vmcnt(12)
	v_lshlrev_b32_e32 v162, 16, v230
	v_and_b32_e32 v163, 0xffff0000, v230
	v_lshlrev_b32_e32 v138, 16, v231
	v_and_b32_e32 v139, 0xffff0000, v231
	v_addc_co_u32_e32 v141, vcc, 0, v129, vcc
	v_pk_fma_f32 v[114:115], v[130:131], s[38:39], v[114:115] op_sel_hi:[1,0,1]
	v_pk_fma_f32 v[112:113], v[142:143], s[38:39], v[112:113] op_sel_hi:[1,0,1]
	v_pk_fma_f32 v[78:79], v[134:135], s[38:39], v[78:79] op_sel_hi:[1,0,1]
	v_pk_fma_f32 v[76:77], v[144:145], s[38:39], v[76:77] op_sel_hi:[1,0,1]
	v_pk_fma_f32 v[50:51], v[136:137], s[38:39], v[50:51] op_sel_hi:[1,0,1]
	v_pk_fma_f32 v[48:49], v[146:147], s[38:39], v[48:49] op_sel_hi:[1,0,1]
	v_pk_fma_f32 v[26:27], v[138:139], s[38:39], v[26:27] op_sel_hi:[1,0,1]
	v_pk_fma_f32 v[24:25], v[162:163], s[38:39], v[24:25] op_sel_hi:[1,0,1]
	s_nop 0
	v_add_co_u32_e32 v140, vcc, s80, v128
	s_waitcnt vmcnt(11)
	v_lshlrev_b32_e32 v142, 16, v232
	v_and_b32_e32 v143, 0xffff0000, v232
	v_lshlrev_b32_e32 v130, 16, v233
	v_and_b32_e32 v131, 0xffff0000, v233
	s_waitcnt vmcnt(10)
	v_lshlrev_b32_e32 v144, 16, v234
	v_and_b32_e32 v145, 0xffff0000, v234
	v_lshlrev_b32_e32 v134, 16, v235
	v_and_b32_e32 v135, 0xffff0000, v235
	s_waitcnt vmcnt(9)
	v_lshlrev_b32_e32 v146, 16, v236
	v_and_b32_e32 v147, 0xffff0000, v236
	v_lshlrev_b32_e32 v136, 16, v237
	v_and_b32_e32 v137, 0xffff0000, v237
	s_waitcnt vmcnt(8)
	v_lshlrev_b32_e32 v162, 16, v238
	v_and_b32_e32 v163, 0xffff0000, v238
	v_lshlrev_b32_e32 v138, 16, v239
	v_and_b32_e32 v139, 0xffff0000, v239
	v_pk_fma_f32 v[126:127], v[130:131], s[38:39], v[126:127] op_sel_hi:[1,0,1]
	v_pk_fma_f32 v[124:125], v[142:143], s[38:39], v[124:125] op_sel_hi:[1,0,1]
	v_pk_fma_f32 v[90:91], v[134:135], s[38:39], v[90:91] op_sel_hi:[1,0,1]
	v_pk_fma_f32 v[88:89], v[144:145], s[38:39], v[88:89] op_sel_hi:[1,0,1]
	v_pk_fma_f32 v[62:63], v[136:137], s[38:39], v[62:63] op_sel_hi:[1,0,1]
	v_pk_fma_f32 v[60:61], v[146:147], s[38:39], v[60:61] op_sel_hi:[1,0,1]
	v_pk_fma_f32 v[38:39], v[138:139], s[38:39], v[38:39] op_sel_hi:[1,0,1]
	v_pk_fma_f32 v[36:37], v[162:163], s[38:39], v[36:37] op_sel_hi:[1,0,1]
	v_addc_co_u32_e32 v141, vcc, 0, v129, vcc
	s_nop 0
	v_and_b32_e32 v131, 64, v182
	v_xor_b32_e32 v130, 16, v182
	v_add_u32_e32 v131, 64, v131
	v_cmp_lt_i32_e32 vcc, v130, v131
	v_mov_b32_e32 v142, v57
	v_mov_b32_e32 v143, v58
	v_cndmask_b32_e32 v130, v182, v130, vcc
	v_add_co_u32_e32 v128, vcc, s81, v128
	v_mov_b32_e32 v144, v56
	s_nop 0
	v_addc_co_u32_e32 v129, vcc, 0, v129, vcc
	v_mov_b32_e32 v145, v59
	v_pk_add_f32 v[142:143], v[142:143], v[144:145]
	v_mov_b32_e32 v146, v33
	v_mov_b32_e32 v147, v34
	v_lshlrev_b32_e32 v130, 2, v130
	s_waitcnt vmcnt(7)
; __device__ __forceinline__ float bf_lo(unsigned w) { return __uint_as_float(w << 16); }
; __device__ __forceinline__ float bf_hi(unsigned w) { return __uint_as_float(w & 0xffff0000u); }
;     __device__ __forceinline__ bool run(const pg8::f32x4 (&v)[2][2][4][2], const pg8::Unit& u, int wr, int wc, int fr, int fq, LAS unsigned char* sl, int wid, int lane) const {
;     ...
;         for (int ai = 0; ai < 2; ++ai)
; #pragma unroll
;             for (int m = 0; m < 4; ++m) {
;                 float s = 0.f;
; #pragma unroll
;                 for (int bj = 0; bj < 2; ++bj)
; #pragma unroll
;                     for (int n = 0; n < 2; ++n) { const pg8::f32x4 x = v[ai][bj][m][n]; s += (x[0] + x[1]) + (x[2] + x[3]); }
;                 s += __shfl_xor(s, 16); s += __shfl_xor(s, 32);
;                 const float mw = s * (1.0f / 64.0f); float q = 0.f;
; #pragma unroll
;                 for (int bj = 0; bj < 2; ++bj)
; #pragma unroll
;                     for (int n = 0; n < 2; ++n) { const pg8::f32x4 d = v[ai][bj][m][n] - mw; q += (d[0] * d[0] + d[1] * d[1]) + (d[2] * d[2] + d[3] * d[3]); }
;                 q += __shfl_xor(q, 16); q += __shfl_xor(q, 32);
;                 if (fq == 0) P[(ai * 128 + wr * 64 + m * 16 + fr) * 4 + wc] = (f32x2v){mw, q};
;     __device__ __forceinline__ void operator()(pg8::f32x4 (&acc)[2][2][4][2], const pg8::Unit& u, int wr, int wc, int fr, int fq) const {
;     ...
;                     for (int n = 0; n < 2; ++n) { const size_t o_ = off0 + (size_t)(ai * 128 + m * 16) * DM + bj * 128 + n * 16; pg8::f32x4 bs;
;                         if (BASE_BF16) { const v2u w = *(const v2u*)((const bf16*)basev + o_); bs = (pg8::f32x4){pg8::bf_lo(w.x), pg8::bf_hi(w.x), pg8::bf_lo(w.y), pg8::bf_hi(w.y)}; }
;                         else bs = *(const pg8::f32x4*)((const float*)basev + o_);
;                         acc[ai][bj][m][n] = bs * ALPHA + acc[ai][bj][m][n]; }
	v_lshlrev_b32_e32 v162, 16, v240
	v_and_b32_e32 v163, 0xffff0000, v240
	v_lshlrev_b32_e32 v134, 16, v241
	v_and_b32_e32 v135, 0xffff0000, v241
	s_waitcnt vmcnt(6)
	v_lshlrev_b32_e32 v164, 16, v242
	v_and_b32_e32 v165, 0xffff0000, v242
	v_lshlrev_b32_e32 v136, 16, v243
	v_and_b32_e32 v137, 0xffff0000, v243
	s_waitcnt vmcnt(5)
	v_lshlrev_b32_e32 v166, 16, v244
	v_and_b32_e32 v167, 0xffff0000, v244
	v_lshlrev_b32_e32 v138, 16, v245
	v_and_b32_e32 v139, 0xffff0000, v245
	s_waitcnt vmcnt(4)
	v_lshlrev_b32_e32 v168, 16, v246
	v_and_b32_e32 v169, 0xffff0000, v246
	v_lshlrev_b32_e32 v140, 16, v247
	v_and_b32_e32 v141, 0xffff0000, v247
	v_pk_fma_f32 v[122:123], v[134:135], s[38:39], v[122:123] op_sel_hi:[1,0,1]
	v_pk_fma_f32 v[120:121], v[162:163], s[38:39], v[120:121] op_sel_hi:[1,0,1]
	v_pk_fma_f32 v[118:119], v[136:137], s[38:39], v[118:119] op_sel_hi:[1,0,1]
	v_pk_fma_f32 v[116:117], v[164:165], s[38:39], v[116:117] op_sel_hi:[1,0,1]
	v_pk_fma_f32 v[98:99], v[138:139], s[38:39], v[98:99] op_sel_hi:[1,0,1]
	v_pk_fma_f32 v[96:97], v[166:167], s[38:39], v[96:97] op_sel_hi:[1,0,1]
	v_pk_fma_f32 v[70:71], v[140:141], s[38:39], v[70:71] op_sel_hi:[1,0,1]
	v_pk_fma_f32 v[68:69], v[168:169], s[38:39], v[68:69] op_sel_hi:[1,0,1]
	v_mov_b32_e32 v134, v32
	v_mov_b32_e32 v135, v35
	v_add_f32_e32 v141, v12, v13
	v_add_f32_e32 v163, v14, v15
	v_mov_b32_e32 v140, v0
	v_mov_b32_e32 v162, v1
	v_pk_add_f32 v[128:129], v[146:147], v[134:135]
	v_pk_add_f32 v[134:135], v[140:141], v[162:163]
	v_add_f32_e32 v140, v142, v143
	v_pk_add_f32 v[128:129], v[128:129], v[128:129] op_sel_hi:[0,1]
	v_mov_b32_e32 v166, v3
	v_add_f32_e32 v167, 0, v140
	v_mov_b32_e32 v128, v2
	v_pk_add_f32 v[128:129], v[128:129], v[166:167]
	s_nop 0
	v_pk_add_f32 v[128:129], v[134:135], v[128:129]
	s_nop 0
	v_add_f32_e32 v129, v128, v129
	v_mov_b32_e32 v134, v129
	s_nop 1
	v_permlane16_swap_b32_e32 v134, v129
	v_xor_b32_e32 v128, 32, v182
	v_cmp_lt_i32_e32 vcc, v128, v131
	s_waitcnt lgkmcnt(0)
	v_add_f32_e32 v129, v129, v134
	v_cndmask_b32_e32 v128, v182, v128, vcc
	v_lshlrev_b32_e32 v128, 2, v128
	v_mov_b32_e32 v131, v129
	s_nop 1
	v_permlane32_swap_b32_e32 v131, v129
	s_waitcnt lgkmcnt(0)
	v_add_f32_e32 v129, v129, v131
	v_fmamk_f32 v134, v129, 0xbc800000, v59
	v_fmamk_f32 v140, v129, 0xbc800000, v57
	v_fmamk_f32 v142, v129, 0xbc800000, v35
	v_fmamk_f32 v146, v129, 0xbc800000, v33
	v_fmamk_f32 v131, v129, 0xbc800000, v58
	v_fmamk_f32 v135, v129, 0xbc800000, v56
	v_fmamk_f32 v141, v129, 0xbc800000, v34
	v_fmamk_f32 v143, v129, 0xbc800000, v32
	v_fmamk_f32 v162, v129, 0xbc800000, v15
	v_fmamk_f32 v166, v129, 0xbc800000, v13
	v_mul_f32_e32 v140, v140, v140
	v_mul_f32_e32 v134, v134, v134
	v_mul_f32_e32 v146, v146, v146
	v_mul_f32_e32 v142, v142, v142
	v_fmamk_f32 v147, v129, 0xbc800000, v14
	v_fmamk_f32 v163, v129, 0xbc800000, v12
	v_fmamk_f32 v168, v129, 0xbc800000, v3
	v_fmamk_f32 v170, v129, 0xbc800000, v1
	v_mul_f32_e32 v166, v166, v166
	v_mul_f32_e32 v162, v162, v162
	v_fmac_f32_e32 v140, v135, v135
	v_fmac_f32_e32 v134, v131, v131
	v_fmac_f32_e32 v146, v143, v143
	v_fmac_f32_e32 v142, v141, v141
	v_fmamk_f32 v167, v129, 0xbc800000, v2
	v_fmamk_f32 v169, v129, 0xbc800000, v0
	v_mul_f32_e32 v170, v170, v170
	v_mul_f32_e32 v168, v168, v168
	v_fmac_f32_e32 v166, v163, v163
	v_fmac_f32_e32 v162, v147, v147
	v_add_f32_e32 v131, v140, v134
	v_add_f32_e32 v134, v146, v142
	v_fmac_f32_e32 v170, v169, v169
	v_fmac_f32_e32 v168, v167, v167
	v_add_f32_e32 v135, v166, v162
	v_add_f32_e32 v131, v131, v134
	v_add_f32_e32 v140, v170, v168
	v_add_f32_e32 v131, v135, v131
	v_add_f32_e32 v131, v140, v131
	v_mov_b32_e32 v134, v131
	s_nop 1
	v_permlane16_swap_b32_e32 v134, v131
	s_waitcnt lgkmcnt(0)
	v_add_f32_e32 v131, v131, v134
	v_mov_b32_e32 v134, v131
	s_nop 1
	v_permlane32_swap_b32_e32 v134, v131
	s_waitcnt vmcnt(3)
	v_lshlrev_b32_e32 v140, 16, v248
	v_and_b32_e32 v141, 0xffff0000, v248
	v_lshlrev_b32_e32 v136, 16, v249
	v_and_b32_e32 v137, 0xffff0000, v249
	s_waitcnt vmcnt(2)
	v_lshlrev_b32_e32 v142, 16, v250
	v_and_b32_e32 v143, 0xffff0000, v250
	v_lshlrev_b32_e32 v138, 16, v251
	v_and_b32_e32 v139, 0xffff0000, v251
	s_waitcnt vmcnt(1)
	v_lshlrev_b32_e32 v146, 16, v252
	v_and_b32_e32 v147, 0xffff0000, v252
	v_lshlrev_b32_e32 v162, 16, v253
	v_and_b32_e32 v163, 0xffff0000, v253
	s_waitcnt vmcnt(0)
	v_lshlrev_b32_e32 v164, 16, v254
	v_and_b32_e32 v165, 0xffff0000, v254
	v_lshlrev_b32_e32 v144, 16, v255
	v_and_b32_e32 v145, 0xffff0000, v255
	v_pk_fma_f32 v[106:107], v[136:137], s[38:39], v[106:107] op_sel_hi:[1,0,1]
	v_pk_fma_f32 v[104:105], v[140:141], s[38:39], v[104:105] op_sel_hi:[1,0,1]
	v_pk_fma_f32 v[102:103], v[138:139], s[38:39], v[102:103] op_sel_hi:[1,0,1]
	v_pk_fma_f32 v[100:101], v[142:143], s[38:39], v[100:101] op_sel_hi:[1,0,1]
	v_pk_fma_f32 v[94:95], v[162:163], s[38:39], v[94:95] op_sel_hi:[1,0,1]
	v_pk_fma_f32 v[92:93], v[146:147], s[38:39], v[92:93] op_sel_hi:[1,0,1]
	v_pk_fma_f32 v[82:83], v[144:145], s[38:39], v[82:83] op_sel_hi:[1,0,1]
	v_pk_fma_f32 v[80:81], v[164:165], s[38:39], v[80:81] op_sel_hi:[1,0,1]
	s_nop 0
	s_and_saveexec_b64 s[54:55], s[0:1]
	s_cbranch_execz .LBB0_1819
	v_mul_f32_e32 v136, 0x3c800000, v129
	s_waitcnt lgkmcnt(0)
	v_add_f32_e32 v137, v131, v134
	ds_write_b64 v187, v[136:137]
